# P0: write-through on the transposed W_in bf16 stores (whole 128-byte lines per row) so barrier 1 flushes less
# baseline (speedup 1.0000x reference)
.LBB0_74:
	ds_read2_b32 v[198:199], v153 offset0:65 offset1:130
	ds_read2_b32 v[200:201], v164 offset0:67 offset1:132
	ds_read2_b32 v[202:203], v163 offset0:69 offset1:134
	ds_read_b32 v204, v153 offset:1820
	s_ashr_i32 s9, s8, 31
	s_waitcnt lgkmcnt(3)
	v_cvt_pk_bf16_f32 v196, v196, v198
	s_waitcnt lgkmcnt(2)
	v_cvt_pk_bf16_f32 v197, v199, v200
	s_waitcnt lgkmcnt(1)
	v_cvt_pk_bf16_f32 v198, v201, v202
	v_mad_u64_u32 v[200:201], s[4:5], s16, v130, 0
	v_mov_b32_e32 v130, v201
	s_waitcnt lgkmcnt(0)
	v_cvt_pk_bf16_f32 v199, v203, v204
	v_mad_u64_u32 v[202:203], s[4:5], s16, v135, v[130:131]
	v_mov_b32_e32 v201, v202
	v_lshl_add_u64 v[200:201], v[200:201], 1, s[14:15]
	v_lshl_add_u64 v[200:201], s[8:9], 1, v[200:201]
	v_mov_b32_e32 v135, v131
	v_lshl_add_u64 v[200:201], v[200:201], 0, v[134:135]
	global_store_dwordx4 v[200:201], v[196:199], off sc1

.LBB0_77:
	ds_read2_b32 v[198:199], v153 offset0:73 offset1:138
	ds_read2_b32 v[200:201], v164 offset0:75 offset1:140
	ds_read2_b32 v[202:203], v163 offset0:77 offset1:142
	ds_read_b32 v204, v153 offset:1852
	s_ashr_i32 s9, s8, 31
	s_waitcnt lgkmcnt(3)
	v_cvt_pk_bf16_f32 v196, v196, v198
	s_waitcnt lgkmcnt(2)
	v_cvt_pk_bf16_f32 v197, v199, v200
	s_waitcnt lgkmcnt(1)
	v_cvt_pk_bf16_f32 v198, v201, v202
	v_mad_u64_u32 v[200:201], s[0:1], s16, v135, 0
	v_mov_b32_e32 v202, v201
	s_waitcnt lgkmcnt(0)
	v_cvt_pk_bf16_f32 v199, v203, v204
	v_mad_u64_u32 v[202:203], s[0:1], s16, v130, v[202:203]
	v_mov_b32_e32 v201, v202
	v_lshl_add_u64 v[200:201], v[200:201], 1, s[14:15]
	v_lshl_add_u64 v[200:201], s[8:9], 1, v[200:201]
	v_mov_b32_e32 v135, v131
	v_lshl_add_u64 v[200:201], v[200:201], 0, v[134:135]
	global_store_dwordx4 v[200:201], v[196:199], off sc1

.LBB0_80:
	ds_read2_b32 v[198:199], v153 offset0:81 offset1:146
	ds_read2_b32 v[200:201], v164 offset0:83 offset1:148
	ds_read2_b32 v[202:203], v163 offset0:85 offset1:150
	ds_read_b32 v204, v153 offset:1884
	s_ashr_i32 s9, s8, 31
	s_waitcnt lgkmcnt(3)
	v_cvt_pk_bf16_f32 v196, v196, v198
	s_waitcnt lgkmcnt(2)
	v_cvt_pk_bf16_f32 v197, v199, v200
	s_waitcnt lgkmcnt(1)
	v_cvt_pk_bf16_f32 v198, v201, v202
	v_mad_u64_u32 v[200:201], s[0:1], s16, v135, 0
	v_mov_b32_e32 v202, v201
	s_waitcnt lgkmcnt(0)
	v_cvt_pk_bf16_f32 v199, v203, v204
	v_mad_u64_u32 v[202:203], s[0:1], s16, v130, v[202:203]
	v_mov_b32_e32 v201, v202
	v_lshl_add_u64 v[200:201], v[200:201], 1, s[14:15]
	v_lshl_add_u64 v[200:201], s[8:9], 1, v[200:201]
	v_mov_b32_e32 v135, v131
	v_lshl_add_u64 v[200:201], v[200:201], 0, v[134:135]
	global_store_dwordx4 v[200:201], v[196:199], off sc1

.LBB0_83:
	ds_read2_b32 v[198:199], v153 offset0:89 offset1:154
	ds_read2_b32 v[200:201], v164 offset0:91 offset1:156
	ds_read2_b32 v[202:203], v163 offset0:93 offset1:158
	ds_read_b32 v204, v153 offset:1916
	s_ashr_i32 s9, s8, 31
	s_waitcnt lgkmcnt(3)
	v_cvt_pk_bf16_f32 v196, v196, v198
	s_waitcnt lgkmcnt(2)
	v_cvt_pk_bf16_f32 v197, v199, v200
	s_waitcnt lgkmcnt(1)
	v_cvt_pk_bf16_f32 v198, v201, v202
	v_mad_u64_u32 v[200:201], s[0:1], s16, v135, 0
	v_mov_b32_e32 v202, v201
	s_waitcnt lgkmcnt(0)
	v_cvt_pk_bf16_f32 v199, v203, v204
	v_mad_u64_u32 v[202:203], s[0:1], s16, v130, v[202:203]
	v_mov_b32_e32 v201, v202
	v_lshl_add_u64 v[200:201], v[200:201], 1, s[14:15]
	v_lshl_add_u64 v[200:201], s[8:9], 1, v[200:201]
	v_mov_b32_e32 v135, v131
	v_lshl_add_u64 v[200:201], v[200:201], 0, v[134:135]
	global_store_dwordx4 v[200:201], v[196:199], off sc1

.LBB0_86:
	ds_read2_b32 v[198:199], v153 offset0:97 offset1:162
	ds_read2_b32 v[200:201], v164 offset0:99 offset1:164
	ds_read2_b32 v[202:203], v163 offset0:101 offset1:166
	ds_read_b32 v204, v153 offset:1948
	s_ashr_i32 s9, s8, 31
	s_waitcnt lgkmcnt(3)
	v_cvt_pk_bf16_f32 v196, v196, v198
	s_waitcnt lgkmcnt(2)
	v_cvt_pk_bf16_f32 v197, v199, v200
	s_waitcnt lgkmcnt(1)
	v_cvt_pk_bf16_f32 v198, v201, v202
	v_mad_u64_u32 v[200:201], s[0:1], s16, v135, 0
	v_mov_b32_e32 v202, v201
	s_waitcnt lgkmcnt(0)
	v_cvt_pk_bf16_f32 v199, v203, v204
	v_mad_u64_u32 v[202:203], s[0:1], s16, v130, v[202:203]
	v_mov_b32_e32 v201, v202
	v_lshl_add_u64 v[200:201], v[200:201], 1, s[14:15]
	v_lshl_add_u64 v[200:201], s[8:9], 1, v[200:201]
	v_mov_b32_e32 v135, v131
	v_lshl_add_u64 v[200:201], v[200:201], 0, v[134:135]
	global_store_dwordx4 v[200:201], v[196:199], off sc1

.LBB0_89:
	ds_read2_b32 v[198:199], v153 offset0:105 offset1:170
	ds_read2_b32 v[200:201], v164 offset0:107 offset1:172
	ds_read2_b32 v[202:203], v163 offset0:109 offset1:174
	ds_read_b32 v204, v153 offset:1980
	s_ashr_i32 s9, s8, 31
	s_waitcnt lgkmcnt(3)
	v_cvt_pk_bf16_f32 v196, v196, v198
	s_waitcnt lgkmcnt(2)
	v_cvt_pk_bf16_f32 v197, v199, v200
	s_waitcnt lgkmcnt(1)
	v_cvt_pk_bf16_f32 v198, v201, v202
	v_mad_u64_u32 v[200:201], s[0:1], s16, v135, 0
	v_mov_b32_e32 v202, v201
	s_waitcnt lgkmcnt(0)
	v_cvt_pk_bf16_f32 v199, v203, v204
	v_mad_u64_u32 v[202:203], s[0:1], s16, v130, v[202:203]
	v_mov_b32_e32 v201, v202
	v_lshl_add_u64 v[200:201], v[200:201], 1, s[14:15]
	v_lshl_add_u64 v[200:201], s[8:9], 1, v[200:201]
	v_mov_b32_e32 v135, v131
	v_lshl_add_u64 v[200:201], v[200:201], 0, v[134:135]
	global_store_dwordx4 v[200:201], v[196:199], off sc1

.LBB0_92:
	ds_read2_b32 v[198:199], v153 offset0:113 offset1:178
	ds_read2_b32 v[200:201], v164 offset0:115 offset1:180
	ds_read2_b32 v[202:203], v163 offset0:117 offset1:182
	ds_read_b32 v204, v153 offset:2012
	s_ashr_i32 s9, s8, 31
	s_waitcnt lgkmcnt(3)
	v_cvt_pk_bf16_f32 v196, v196, v198
	s_waitcnt lgkmcnt(2)
	v_cvt_pk_bf16_f32 v197, v199, v200
	s_waitcnt lgkmcnt(1)
	v_cvt_pk_bf16_f32 v198, v201, v202
	v_mad_u64_u32 v[200:201], s[0:1], s16, v135, 0
	v_mov_b32_e32 v202, v201
	s_waitcnt lgkmcnt(0)
	v_cvt_pk_bf16_f32 v199, v203, v204
	v_mad_u64_u32 v[202:203], s[0:1], s16, v130, v[202:203]
	v_mov_b32_e32 v201, v202
	v_lshl_add_u64 v[200:201], v[200:201], 1, s[14:15]
	v_lshl_add_u64 v[200:201], s[8:9], 1, v[200:201]
	v_mov_b32_e32 v135, v131
	v_lshl_add_u64 v[200:201], v[200:201], 0, v[134:135]
	global_store_dwordx4 v[200:201], v[196:199], off sc1

.LBB0_95:
	ds_read2_b32 v[198:199], v153 offset0:121 offset1:186
	ds_read2_b32 v[200:201], v164 offset0:123 offset1:188
	ds_read2_b32 v[202:203], v163 offset0:125 offset1:190
	ds_read_b32 v204, v153 offset:2044
	s_ashr_i32 s9, s8, 31
	s_waitcnt lgkmcnt(3)
	v_cvt_pk_bf16_f32 v196, v196, v198
	s_waitcnt lgkmcnt(2)
	v_cvt_pk_bf16_f32 v197, v199, v200
	s_waitcnt lgkmcnt(1)
	v_cvt_pk_bf16_f32 v198, v201, v202
	v_mad_u64_u32 v[200:201], s[0:1], s16, v135, 0
	v_mov_b32_e32 v202, v201
	s_waitcnt lgkmcnt(0)
	v_cvt_pk_bf16_f32 v199, v203, v204
	v_mad_u64_u32 v[202:203], s[0:1], s16, v130, v[202:203]
	v_mov_b32_e32 v201, v202
	v_lshl_add_u64 v[200:201], v[200:201], 1, s[14:15]
	v_lshl_add_u64 v[200:201], s[8:9], 1, v[200:201]
	v_mov_b32_e32 v135, v131
	v_lshl_add_u64 v[200:201], v[200:201], 0, v[134:135]
	global_store_dwordx4 v[200:201], v[196:199], off sc1

.LBB0_122:
	ds_read2_b32 v[166:167], v153 offset0:65 offset1:130
	ds_read2_b32 v[168:169], v164 offset0:67 offset1:132
	ds_read2_b32 v[170:171], v163 offset0:69 offset1:134
	ds_read_b32 v172, v153 offset:1820
	s_ashr_i32 s87, s86, 31
	s_waitcnt lgkmcnt(3)
	v_cvt_pk_bf16_f32 v166, v165, v166
	s_waitcnt lgkmcnt(2)
	v_cvt_pk_bf16_f32 v167, v167, v168
	s_waitcnt lgkmcnt(1)
	v_cvt_pk_bf16_f32 v168, v169, v170
	s_waitcnt lgkmcnt(0)
	v_cvt_pk_bf16_f32 v169, v171, v172
	v_mad_u64_u32 v[170:171], s[4:5], s27, v135, 0
	v_mov_b32_e32 v172, v171
	v_mad_u64_u32 v[172:173], s[4:5], s27, v130, v[172:173]
	v_mov_b32_e32 v171, v172
	v_lshl_add_u64 v[170:171], v[170:171], 1, s[88:89]
	v_lshl_add_u64 v[170:171], s[86:87], 1, v[170:171]
	v_mov_b32_e32 v135, v131
	v_lshl_add_u64 v[170:171], v[170:171], 0, v[134:135]
	global_store_dwordx4 v[170:171], v[166:169], off sc1

.LBB0_125:
	ds_read2_b32 v[166:167], v153 offset0:73 offset1:138
	ds_read2_b32 v[168:169], v164 offset0:75 offset1:140
	ds_read2_b32 v[170:171], v163 offset0:77 offset1:142
	ds_read_b32 v172, v153 offset:1852
	s_ashr_i32 s87, s86, 31
	s_waitcnt lgkmcnt(3)
	v_cvt_pk_bf16_f32 v166, v165, v166
	s_waitcnt lgkmcnt(2)
	v_cvt_pk_bf16_f32 v167, v167, v168
	s_waitcnt lgkmcnt(1)
	v_cvt_pk_bf16_f32 v168, v169, v170
	s_waitcnt lgkmcnt(0)
	v_cvt_pk_bf16_f32 v169, v171, v172
	v_mad_u64_u32 v[170:171], s[0:1], s27, v135, 0
	v_mov_b32_e32 v172, v171
	v_mad_u64_u32 v[172:173], s[0:1], s27, v130, v[172:173]
	v_mov_b32_e32 v171, v172
	v_lshl_add_u64 v[170:171], v[170:171], 1, s[88:89]
	v_lshl_add_u64 v[170:171], s[86:87], 1, v[170:171]
	v_mov_b32_e32 v135, v131
	v_lshl_add_u64 v[170:171], v[170:171], 0, v[134:135]
	global_store_dwordx4 v[170:171], v[166:169], off sc1

.LBB0_128:
	ds_read2_b32 v[166:167], v153 offset0:81 offset1:146
	ds_read2_b32 v[168:169], v164 offset0:83 offset1:148
	ds_read2_b32 v[170:171], v163 offset0:85 offset1:150
	ds_read_b32 v172, v153 offset:1884
	s_ashr_i32 s87, s86, 31
	s_waitcnt lgkmcnt(3)
	v_cvt_pk_bf16_f32 v166, v165, v166
	s_waitcnt lgkmcnt(2)
	v_cvt_pk_bf16_f32 v167, v167, v168
	s_waitcnt lgkmcnt(1)
	v_cvt_pk_bf16_f32 v168, v169, v170
	s_waitcnt lgkmcnt(0)
	v_cvt_pk_bf16_f32 v169, v171, v172
	v_mad_u64_u32 v[170:171], s[0:1], s27, v135, 0
	v_mov_b32_e32 v172, v171
	v_mad_u64_u32 v[172:173], s[0:1], s27, v130, v[172:173]
	v_mov_b32_e32 v171, v172
	v_lshl_add_u64 v[170:171], v[170:171], 1, s[88:89]
	v_lshl_add_u64 v[170:171], s[86:87], 1, v[170:171]
	v_mov_b32_e32 v135, v131
	v_lshl_add_u64 v[170:171], v[170:171], 0, v[134:135]
	global_store_dwordx4 v[170:171], v[166:169], off sc1

.LBB0_131:
	ds_read2_b32 v[166:167], v153 offset0:89 offset1:154
	ds_read2_b32 v[168:169], v164 offset0:91 offset1:156
	ds_read2_b32 v[170:171], v163 offset0:93 offset1:158
	ds_read_b32 v172, v153 offset:1916
	s_ashr_i32 s87, s86, 31
	s_waitcnt lgkmcnt(3)
	v_cvt_pk_bf16_f32 v166, v165, v166
	s_waitcnt lgkmcnt(2)
	v_cvt_pk_bf16_f32 v167, v167, v168
	s_waitcnt lgkmcnt(1)
	v_cvt_pk_bf16_f32 v168, v169, v170
	s_waitcnt lgkmcnt(0)
	v_cvt_pk_bf16_f32 v169, v171, v172
	v_mad_u64_u32 v[170:171], s[0:1], s27, v135, 0
	v_mov_b32_e32 v172, v171
	v_mad_u64_u32 v[172:173], s[0:1], s27, v130, v[172:173]
	v_mov_b32_e32 v171, v172
	v_lshl_add_u64 v[170:171], v[170:171], 1, s[88:89]
	v_lshl_add_u64 v[170:171], s[86:87], 1, v[170:171]
	v_mov_b32_e32 v135, v131
	v_lshl_add_u64 v[170:171], v[170:171], 0, v[134:135]
	global_store_dwordx4 v[170:171], v[166:169], off sc1

.LBB0_134:
	ds_read2_b32 v[166:167], v153 offset0:97 offset1:162
	ds_read2_b32 v[168:169], v164 offset0:99 offset1:164
	ds_read2_b32 v[170:171], v163 offset0:101 offset1:166
	ds_read_b32 v172, v153 offset:1948
	s_ashr_i32 s87, s86, 31
	s_waitcnt lgkmcnt(3)
	v_cvt_pk_bf16_f32 v166, v165, v166
	s_waitcnt lgkmcnt(2)
	v_cvt_pk_bf16_f32 v167, v167, v168
	s_waitcnt lgkmcnt(1)
	v_cvt_pk_bf16_f32 v168, v169, v170
	s_waitcnt lgkmcnt(0)
	v_cvt_pk_bf16_f32 v169, v171, v172
	v_mad_u64_u32 v[170:171], s[0:1], s27, v135, 0
	v_mov_b32_e32 v172, v171
	v_mad_u64_u32 v[172:173], s[0:1], s27, v130, v[172:173]
	v_mov_b32_e32 v171, v172
	v_lshl_add_u64 v[170:171], v[170:171], 1, s[88:89]
	v_lshl_add_u64 v[170:171], s[86:87], 1, v[170:171]
	v_mov_b32_e32 v135, v131
	v_lshl_add_u64 v[170:171], v[170:171], 0, v[134:135]
	global_store_dwordx4 v[170:171], v[166:169], off sc1

.LBB0_137:
	ds_read2_b32 v[166:167], v153 offset0:105 offset1:170
	ds_read2_b32 v[168:169], v164 offset0:107 offset1:172
	ds_read2_b32 v[170:171], v163 offset0:109 offset1:174
	ds_read_b32 v172, v153 offset:1980
	s_ashr_i32 s87, s86, 31
	s_waitcnt lgkmcnt(3)
	v_cvt_pk_bf16_f32 v166, v165, v166
	s_waitcnt lgkmcnt(2)
	v_cvt_pk_bf16_f32 v167, v167, v168
	s_waitcnt lgkmcnt(1)
	v_cvt_pk_bf16_f32 v168, v169, v170
	s_waitcnt lgkmcnt(0)
	v_cvt_pk_bf16_f32 v169, v171, v172
	v_mad_u64_u32 v[170:171], s[0:1], s27, v135, 0
	v_mov_b32_e32 v172, v171
	v_mad_u64_u32 v[172:173], s[0:1], s27, v130, v[172:173]
	v_mov_b32_e32 v171, v172
	v_lshl_add_u64 v[170:171], v[170:171], 1, s[88:89]
	v_lshl_add_u64 v[170:171], s[86:87], 1, v[170:171]
	v_mov_b32_e32 v135, v131
	v_lshl_add_u64 v[170:171], v[170:171], 0, v[134:135]
	global_store_dwordx4 v[170:171], v[166:169], off sc1

.LBB0_140:
	ds_read2_b32 v[166:167], v153 offset0:113 offset1:178
	ds_read2_b32 v[168:169], v164 offset0:115 offset1:180
	ds_read2_b32 v[170:171], v163 offset0:117 offset1:182
	ds_read_b32 v172, v153 offset:2012
	s_ashr_i32 s87, s86, 31
	s_waitcnt lgkmcnt(3)
	v_cvt_pk_bf16_f32 v166, v165, v166
	s_waitcnt lgkmcnt(2)
	v_cvt_pk_bf16_f32 v167, v167, v168
	s_waitcnt lgkmcnt(1)
	v_cvt_pk_bf16_f32 v168, v169, v170
	s_waitcnt lgkmcnt(0)
	v_cvt_pk_bf16_f32 v169, v171, v172
	v_mad_u64_u32 v[170:171], s[0:1], s27, v135, 0
	v_mov_b32_e32 v172, v171
	v_mad_u64_u32 v[172:173], s[0:1], s27, v130, v[172:173]
	v_mov_b32_e32 v171, v172
	v_lshl_add_u64 v[170:171], v[170:171], 1, s[88:89]
	v_lshl_add_u64 v[170:171], s[86:87], 1, v[170:171]
	v_mov_b32_e32 v135, v131
	v_lshl_add_u64 v[170:171], v[170:171], 0, v[134:135]
	global_store_dwordx4 v[170:171], v[166:169], off sc1

.LBB0_150:
.LBB0_151:
	ds_read2_b32 v[166:167], v153 offset0:121 offset1:186
	ds_read2_b32 v[168:169], v164 offset0:123 offset1:188
	ds_read2_b32 v[170:171], v163 offset0:125 offset1:190
	ds_read_b32 v163, v153 offset:2044
	s_ashr_i32 s87, s86, 31
	s_waitcnt lgkmcnt(3)
	v_cvt_pk_bf16_f32 v164, v165, v166
	s_waitcnt lgkmcnt(2)
	v_cvt_pk_bf16_f32 v165, v167, v168
	s_waitcnt lgkmcnt(1)
	v_cvt_pk_bf16_f32 v166, v169, v170
	v_mad_u64_u32 v[168:169], s[0:1], s27, v135, 0
	v_mov_b32_e32 v170, v169
	s_waitcnt lgkmcnt(0)
	v_cvt_pk_bf16_f32 v167, v171, v163
	v_mad_u64_u32 v[170:171], s[0:1], s27, v130, v[170:171]
	v_mov_b32_e32 v169, v170
	v_lshl_add_u64 v[168:169], v[168:169], 1, s[88:89]
	v_lshl_add_u64 v[168:169], s[86:87], 1, v[168:169]
	v_mov_b32_e32 v135, v131
	v_lshl_add_u64 v[134:135], v[168:169], 0, v[134:135]
	global_store_dwordx4 v[134:135], v[164:167], off sc1
	s_branch .LBB0_59
